# v16 + packed-math GEMM1 merge-gate epilogue + asymmetric extra barrier so both wave halves overlap their GEMM epilogues
# speedup vs baseline: 1.0090x; 1.0090x over previous
.Lxb_p1_a:
	v_lshl_add_u32 v174, s30, 8, v1
	s_cmp_gt_i32 s12, 3
	s_mov_b64 s[34:35], -1
	s_cbranch_scc0 .LBB0_204
	s_cmp_gt_u32 s12, 7
	s_cbranch_scc0 .LBB0_201
	s_cmp_lt_u32 s12, 16
	s_cbranch_scc0 .LBB0_193
	s_add_i32 s14, s12, -8
	v_lshl_or_b32 v158, s14, 8, v160
	v_lshl_add_u64 v[134:135], v[158:159], 2, s[70:71]
	global_load_dwordx4 v[138:141], v[134:135], off offset:16
	global_load_dwordx4 v[142:145], v[134:135], off
	global_load_dwordx4 v[130:133], v[134:135], off offset:528
	s_nop 0
	global_load_dwordx4 v[134:137], v[134:135], off offset:512
	s_lshl_b32 s15, s30, 3
	s_add_i32 s14, s15, s14
	s_ashr_i32 s15, s14, 31
	s_lshl_b64 s[14:15], s[14:15], 17
	v_readlane_b32 s16, v254, 9
	s_add_u32 s30, s16, s14
	v_readlane_b32 s14, v254, 10
	s_addc_u32 s31, s14, s15
	v_mov_b32_e32 v173, v159
	v_lshl_add_u64 v[176:177], s[30:31], 0, v[172:173]
	s_mov_b64 s[34:35], 0
	s_mov_b32 s14, 0x1000
	s_mov_b32 s15, 0
	s_mov_b32 s100, 0xbfb8aa3b
	s_mov_b32 s101, 0xbfb8aa3b
	s_waitcnt vmcnt(0)
	v_pk_mul_f32 v[130:131], v[130:131], s[100:101]
	v_pk_mul_f32 v[132:133], v[132:133], s[100:101]
	v_pk_mul_f32 v[134:135], v[134:135], s[100:101]
	v_pk_mul_f32 v[136:137], v[136:137], s[100:101]
	v_pk_mul_f32 v[138:139], v[138:139], s[100:101]
	v_pk_mul_f32 v[140:141], v[140:141], s[100:101]
	v_pk_mul_f32 v[142:143], v[142:143], s[100:101]
	v_pk_mul_f32 v[144:145], v[144:145], s[100:101]
	v_pk_fma_f32 v[126:127], v[126:127], s[100:101], v[142:143]
	v_pk_fma_f32 v[128:129], v[128:129], s[100:101], v[144:145]
	v_pk_fma_f32 v[122:123], v[122:123], s[100:101], v[138:139]
	v_pk_fma_f32 v[124:125], v[124:125], s[100:101], v[140:141]
	v_exp_f32_e32 v126, v126
	v_exp_f32_e32 v127, v127
	v_exp_f32_e32 v128, v128
	v_exp_f32_e32 v129, v129
	v_exp_f32_e32 v122, v122
	v_exp_f32_e32 v123, v123
	v_exp_f32_e32 v124, v124
	v_exp_f32_e32 v125, v125
	v_pk_add_f32 v[126:127], v[126:127], 1.0 op_sel_hi:[1,0]
	v_pk_add_f32 v[128:129], v[128:129], 1.0 op_sel_hi:[1,0]
	v_pk_add_f32 v[122:123], v[122:123], 1.0 op_sel_hi:[1,0]
	v_pk_add_f32 v[124:125], v[124:125], 1.0 op_sel_hi:[1,0]
	v_rcp_f32_e32 v126, v126
	v_rcp_f32_e32 v127, v127
	v_rcp_f32_e32 v128, v128
	v_rcp_f32_e32 v129, v129
	v_rcp_f32_e32 v122, v122
	v_rcp_f32_e32 v123, v123
	v_rcp_f32_e32 v124, v124
	v_rcp_f32_e32 v125, v125
	v_cvt_pk_bf16_f32 v146, v126, v127
	v_cvt_pk_bf16_f32 v147, v128, v129
	v_cvt_pk_bf16_f32 v148, v122, v123
	v_cvt_pk_bf16_f32 v149, v124, v125
	global_store_dwordx4 v[176:177], v[146:149], off offset:0
	v_pk_fma_f32 v[118:119], v[118:119], s[100:101], v[134:135]
	v_pk_fma_f32 v[120:121], v[120:121], s[100:101], v[136:137]
	v_pk_fma_f32 v[114:115], v[114:115], s[100:101], v[130:131]
	v_pk_fma_f32 v[116:117], v[116:117], s[100:101], v[132:133]
	v_exp_f32_e32 v118, v118
	v_exp_f32_e32 v119, v119
	v_exp_f32_e32 v120, v120
	v_exp_f32_e32 v121, v121
	v_exp_f32_e32 v114, v114
	v_exp_f32_e32 v115, v115
	v_exp_f32_e32 v116, v116
	v_exp_f32_e32 v117, v117
	v_pk_add_f32 v[118:119], v[118:119], 1.0 op_sel_hi:[1,0]
	v_pk_add_f32 v[120:121], v[120:121], 1.0 op_sel_hi:[1,0]
	v_pk_add_f32 v[114:115], v[114:115], 1.0 op_sel_hi:[1,0]
	v_pk_add_f32 v[116:117], v[116:117], 1.0 op_sel_hi:[1,0]
	v_rcp_f32_e32 v118, v118
	v_rcp_f32_e32 v119, v119
	v_rcp_f32_e32 v120, v120
	v_rcp_f32_e32 v121, v121
	v_rcp_f32_e32 v114, v114
	v_rcp_f32_e32 v115, v115
	v_rcp_f32_e32 v116, v116
	v_rcp_f32_e32 v117, v117
	v_cvt_pk_bf16_f32 v182, v118, v119
	v_cvt_pk_bf16_f32 v183, v120, v121
	v_cvt_pk_bf16_f32 v184, v114, v115
	v_cvt_pk_bf16_f32 v185, v116, v117
	global_store_dwordx4 v[176:177], v[182:185], off offset:1024
	v_pk_fma_f32 v[110:111], v[110:111], s[100:101], v[142:143]
	v_pk_fma_f32 v[112:113], v[112:113], s[100:101], v[144:145]
	v_pk_fma_f32 v[106:107], v[106:107], s[100:101], v[138:139]
	v_pk_fma_f32 v[108:109], v[108:109], s[100:101], v[140:141]
	v_exp_f32_e32 v110, v110
	v_exp_f32_e32 v111, v111
	v_exp_f32_e32 v112, v112
	v_exp_f32_e32 v113, v113
	v_exp_f32_e32 v106, v106
	v_exp_f32_e32 v107, v107
	v_exp_f32_e32 v108, v108
	v_exp_f32_e32 v109, v109
	v_pk_add_f32 v[110:111], v[110:111], 1.0 op_sel_hi:[1,0]
	v_pk_add_f32 v[112:113], v[112:113], 1.0 op_sel_hi:[1,0]
	v_pk_add_f32 v[106:107], v[106:107], 1.0 op_sel_hi:[1,0]
	v_pk_add_f32 v[108:109], v[108:109], 1.0 op_sel_hi:[1,0]
	v_rcp_f32_e32 v110, v110
	v_rcp_f32_e32 v111, v111
	v_rcp_f32_e32 v112, v112
	v_rcp_f32_e32 v113, v113
	v_rcp_f32_e32 v106, v106
	v_rcp_f32_e32 v107, v107
	v_rcp_f32_e32 v108, v108
	v_rcp_f32_e32 v109, v109
	v_cvt_pk_bf16_f32 v146, v110, v111
	v_cvt_pk_bf16_f32 v147, v112, v113
	v_cvt_pk_bf16_f32 v148, v106, v107
	v_cvt_pk_bf16_f32 v149, v108, v109
	global_store_dwordx4 v[176:177], v[146:149], off offset:2048
	v_pk_fma_f32 v[102:103], v[102:103], s[100:101], v[134:135]
	v_pk_fma_f32 v[104:105], v[104:105], s[100:101], v[136:137]
	v_pk_fma_f32 v[98:99], v[98:99], s[100:101], v[130:131]
	v_pk_fma_f32 v[100:101], v[100:101], s[100:101], v[132:133]
	v_exp_f32_e32 v102, v102
	v_exp_f32_e32 v103, v103
	v_exp_f32_e32 v104, v104
	v_exp_f32_e32 v105, v105
	v_exp_f32_e32 v98, v98
	v_exp_f32_e32 v99, v99
	v_exp_f32_e32 v100, v100
	v_exp_f32_e32 v101, v101
	v_pk_add_f32 v[102:103], v[102:103], 1.0 op_sel_hi:[1,0]
	v_pk_add_f32 v[104:105], v[104:105], 1.0 op_sel_hi:[1,0]
	v_pk_add_f32 v[98:99], v[98:99], 1.0 op_sel_hi:[1,0]
	v_pk_add_f32 v[100:101], v[100:101], 1.0 op_sel_hi:[1,0]
	v_rcp_f32_e32 v102, v102
	v_rcp_f32_e32 v103, v103
	v_rcp_f32_e32 v104, v104
	v_rcp_f32_e32 v105, v105
	v_rcp_f32_e32 v98, v98
	v_rcp_f32_e32 v99, v99
	v_rcp_f32_e32 v100, v100
	v_rcp_f32_e32 v101, v101
	v_cvt_pk_bf16_f32 v182, v102, v103
	v_cvt_pk_bf16_f32 v183, v104, v105
	v_cvt_pk_bf16_f32 v184, v98, v99
	v_cvt_pk_bf16_f32 v185, v100, v101
	global_store_dwordx4 v[176:177], v[182:185], off offset:3072
	v_lshl_add_u64 v[176:177], v[176:177], 0, s[14:15]
	v_pk_fma_f32 v[94:95], v[94:95], s[100:101], v[142:143]
	v_pk_fma_f32 v[96:97], v[96:97], s[100:101], v[144:145]
	v_pk_fma_f32 v[90:91], v[90:91], s[100:101], v[138:139]
	v_pk_fma_f32 v[92:93], v[92:93], s[100:101], v[140:141]
	v_exp_f32_e32 v94, v94
	v_exp_f32_e32 v95, v95
	v_exp_f32_e32 v96, v96
	v_exp_f32_e32 v97, v97
	v_exp_f32_e32 v90, v90
	v_exp_f32_e32 v91, v91
	v_exp_f32_e32 v92, v92
	v_exp_f32_e32 v93, v93
	v_pk_add_f32 v[94:95], v[94:95], 1.0 op_sel_hi:[1,0]
	v_pk_add_f32 v[96:97], v[96:97], 1.0 op_sel_hi:[1,0]
	v_pk_add_f32 v[90:91], v[90:91], 1.0 op_sel_hi:[1,0]
	v_pk_add_f32 v[92:93], v[92:93], 1.0 op_sel_hi:[1,0]
	v_rcp_f32_e32 v94, v94
	v_rcp_f32_e32 v95, v95
	v_rcp_f32_e32 v96, v96
	v_rcp_f32_e32 v97, v97
	v_rcp_f32_e32 v90, v90
	v_rcp_f32_e32 v91, v91
	v_rcp_f32_e32 v92, v92
	v_rcp_f32_e32 v93, v93
	v_cvt_pk_bf16_f32 v146, v94, v95
	v_cvt_pk_bf16_f32 v147, v96, v97
	v_cvt_pk_bf16_f32 v148, v90, v91
	v_cvt_pk_bf16_f32 v149, v92, v93
	global_store_dwordx4 v[176:177], v[146:149], off offset:0
	v_pk_fma_f32 v[86:87], v[86:87], s[100:101], v[134:135]
	v_pk_fma_f32 v[88:89], v[88:89], s[100:101], v[136:137]
	v_pk_fma_f32 v[82:83], v[82:83], s[100:101], v[130:131]
	v_pk_fma_f32 v[84:85], v[84:85], s[100:101], v[132:133]
	v_exp_f32_e32 v86, v86
	v_exp_f32_e32 v87, v87
	v_exp_f32_e32 v88, v88
	v_exp_f32_e32 v89, v89
	v_exp_f32_e32 v82, v82
	v_exp_f32_e32 v83, v83
	v_exp_f32_e32 v84, v84
	v_exp_f32_e32 v85, v85
	v_pk_add_f32 v[86:87], v[86:87], 1.0 op_sel_hi:[1,0]
	v_pk_add_f32 v[88:89], v[88:89], 1.0 op_sel_hi:[1,0]
	v_pk_add_f32 v[82:83], v[82:83], 1.0 op_sel_hi:[1,0]
	v_pk_add_f32 v[84:85], v[84:85], 1.0 op_sel_hi:[1,0]
	v_rcp_f32_e32 v86, v86
	v_rcp_f32_e32 v87, v87
	v_rcp_f32_e32 v88, v88
	v_rcp_f32_e32 v89, v89
	v_rcp_f32_e32 v82, v82
	v_rcp_f32_e32 v83, v83
	v_rcp_f32_e32 v84, v84
	v_rcp_f32_e32 v85, v85
	v_cvt_pk_bf16_f32 v182, v86, v87
	v_cvt_pk_bf16_f32 v183, v88, v89
	v_cvt_pk_bf16_f32 v184, v82, v83
	v_cvt_pk_bf16_f32 v185, v84, v85
	global_store_dwordx4 v[176:177], v[182:185], off offset:1024
	v_pk_fma_f32 v[78:79], v[78:79], s[100:101], v[142:143]
	v_pk_fma_f32 v[80:81], v[80:81], s[100:101], v[144:145]
	v_pk_fma_f32 v[74:75], v[74:75], s[100:101], v[138:139]
	v_pk_fma_f32 v[76:77], v[76:77], s[100:101], v[140:141]
	v_exp_f32_e32 v78, v78
	v_exp_f32_e32 v79, v79
	v_exp_f32_e32 v80, v80
	v_exp_f32_e32 v81, v81
	v_exp_f32_e32 v74, v74
	v_exp_f32_e32 v75, v75
	v_exp_f32_e32 v76, v76
	v_exp_f32_e32 v77, v77
	v_pk_add_f32 v[78:79], v[78:79], 1.0 op_sel_hi:[1,0]
	v_pk_add_f32 v[80:81], v[80:81], 1.0 op_sel_hi:[1,0]
	v_pk_add_f32 v[74:75], v[74:75], 1.0 op_sel_hi:[1,0]
	v_pk_add_f32 v[76:77], v[76:77], 1.0 op_sel_hi:[1,0]
	v_rcp_f32_e32 v78, v78
	v_rcp_f32_e32 v79, v79
	v_rcp_f32_e32 v80, v80
	v_rcp_f32_e32 v81, v81
	v_rcp_f32_e32 v74, v74
	v_rcp_f32_e32 v75, v75
	v_rcp_f32_e32 v76, v76
	v_rcp_f32_e32 v77, v77
	v_cvt_pk_bf16_f32 v146, v78, v79
	v_cvt_pk_bf16_f32 v147, v80, v81
	v_cvt_pk_bf16_f32 v148, v74, v75
	v_cvt_pk_bf16_f32 v149, v76, v77
	global_store_dwordx4 v[176:177], v[146:149], off offset:2048
	v_pk_fma_f32 v[70:71], v[70:71], s[100:101], v[134:135]
	v_pk_fma_f32 v[72:73], v[72:73], s[100:101], v[136:137]
	v_pk_fma_f32 v[66:67], v[66:67], s[100:101], v[130:131]
	v_pk_fma_f32 v[68:69], v[68:69], s[100:101], v[132:133]
	v_exp_f32_e32 v70, v70
	v_exp_f32_e32 v71, v71
	v_exp_f32_e32 v72, v72
	v_exp_f32_e32 v73, v73
	v_exp_f32_e32 v66, v66
	v_exp_f32_e32 v67, v67
	v_exp_f32_e32 v68, v68
	v_exp_f32_e32 v69, v69
	v_pk_add_f32 v[70:71], v[70:71], 1.0 op_sel_hi:[1,0]
	v_pk_add_f32 v[72:73], v[72:73], 1.0 op_sel_hi:[1,0]
	v_pk_add_f32 v[66:67], v[66:67], 1.0 op_sel_hi:[1,0]
	v_pk_add_f32 v[68:69], v[68:69], 1.0 op_sel_hi:[1,0]
	v_rcp_f32_e32 v70, v70
	v_rcp_f32_e32 v71, v71
	v_rcp_f32_e32 v72, v72
	v_rcp_f32_e32 v73, v73
	v_rcp_f32_e32 v66, v66
	v_rcp_f32_e32 v67, v67
	v_rcp_f32_e32 v68, v68
	v_rcp_f32_e32 v69, v69
	v_cvt_pk_bf16_f32 v182, v70, v71
	v_cvt_pk_bf16_f32 v183, v72, v73
	v_cvt_pk_bf16_f32 v184, v66, v67
	v_cvt_pk_bf16_f32 v185, v68, v69
	global_store_dwordx4 v[176:177], v[182:185], off offset:3072
	v_lshl_add_u64 v[176:177], v[176:177], 0, s[14:15]
	v_pk_fma_f32 v[62:63], v[62:63], s[100:101], v[142:143]
	v_pk_fma_f32 v[64:65], v[64:65], s[100:101], v[144:145]
	v_pk_fma_f32 v[58:59], v[58:59], s[100:101], v[138:139]
	v_pk_fma_f32 v[60:61], v[60:61], s[100:101], v[140:141]
	v_exp_f32_e32 v62, v62
	v_exp_f32_e32 v63, v63
	v_exp_f32_e32 v64, v64
	v_exp_f32_e32 v65, v65
	v_exp_f32_e32 v58, v58
	v_exp_f32_e32 v59, v59
	v_exp_f32_e32 v60, v60
	v_exp_f32_e32 v61, v61
	v_pk_add_f32 v[62:63], v[62:63], 1.0 op_sel_hi:[1,0]
	v_pk_add_f32 v[64:65], v[64:65], 1.0 op_sel_hi:[1,0]
	v_pk_add_f32 v[58:59], v[58:59], 1.0 op_sel_hi:[1,0]
	v_pk_add_f32 v[60:61], v[60:61], 1.0 op_sel_hi:[1,0]
	v_rcp_f32_e32 v62, v62
	v_rcp_f32_e32 v63, v63
	v_rcp_f32_e32 v64, v64
	v_rcp_f32_e32 v65, v65
	v_rcp_f32_e32 v58, v58
	v_rcp_f32_e32 v59, v59
	v_rcp_f32_e32 v60, v60
	v_rcp_f32_e32 v61, v61
	v_cvt_pk_bf16_f32 v146, v62, v63
	v_cvt_pk_bf16_f32 v147, v64, v65
	v_cvt_pk_bf16_f32 v148, v58, v59
	v_cvt_pk_bf16_f32 v149, v60, v61
	global_store_dwordx4 v[176:177], v[146:149], off offset:0
	v_pk_fma_f32 v[54:55], v[54:55], s[100:101], v[134:135]
	v_pk_fma_f32 v[56:57], v[56:57], s[100:101], v[136:137]
	v_pk_fma_f32 v[50:51], v[50:51], s[100:101], v[130:131]
	v_pk_fma_f32 v[52:53], v[52:53], s[100:101], v[132:133]
	v_exp_f32_e32 v54, v54
	v_exp_f32_e32 v55, v55
	v_exp_f32_e32 v56, v56
	v_exp_f32_e32 v57, v57
	v_exp_f32_e32 v50, v50
	v_exp_f32_e32 v51, v51
	v_exp_f32_e32 v52, v52
	v_exp_f32_e32 v53, v53
	v_pk_add_f32 v[54:55], v[54:55], 1.0 op_sel_hi:[1,0]
	v_pk_add_f32 v[56:57], v[56:57], 1.0 op_sel_hi:[1,0]
	v_pk_add_f32 v[50:51], v[50:51], 1.0 op_sel_hi:[1,0]
	v_pk_add_f32 v[52:53], v[52:53], 1.0 op_sel_hi:[1,0]
	v_rcp_f32_e32 v54, v54
	v_rcp_f32_e32 v55, v55
	v_rcp_f32_e32 v56, v56
	v_rcp_f32_e32 v57, v57
	v_rcp_f32_e32 v50, v50
	v_rcp_f32_e32 v51, v51
	v_rcp_f32_e32 v52, v52
	v_rcp_f32_e32 v53, v53
	v_cvt_pk_bf16_f32 v182, v54, v55
	v_cvt_pk_bf16_f32 v183, v56, v57
	v_cvt_pk_bf16_f32 v184, v50, v51
	v_cvt_pk_bf16_f32 v185, v52, v53
	global_store_dwordx4 v[176:177], v[182:185], off offset:1024
	v_pk_fma_f32 v[46:47], v[46:47], s[100:101], v[142:143]
	v_pk_fma_f32 v[48:49], v[48:49], s[100:101], v[144:145]
	v_pk_fma_f32 v[42:43], v[42:43], s[100:101], v[138:139]
	v_pk_fma_f32 v[44:45], v[44:45], s[100:101], v[140:141]
	v_exp_f32_e32 v46, v46
	v_exp_f32_e32 v47, v47
	v_exp_f32_e32 v48, v48
	v_exp_f32_e32 v49, v49
	v_exp_f32_e32 v42, v42
	v_exp_f32_e32 v43, v43
	v_exp_f32_e32 v44, v44
	v_exp_f32_e32 v45, v45
	v_pk_add_f32 v[46:47], v[46:47], 1.0 op_sel_hi:[1,0]
	v_pk_add_f32 v[48:49], v[48:49], 1.0 op_sel_hi:[1,0]
	v_pk_add_f32 v[42:43], v[42:43], 1.0 op_sel_hi:[1,0]
	v_pk_add_f32 v[44:45], v[44:45], 1.0 op_sel_hi:[1,0]
	v_rcp_f32_e32 v46, v46
	v_rcp_f32_e32 v47, v47
	v_rcp_f32_e32 v48, v48
	v_rcp_f32_e32 v49, v49
	v_rcp_f32_e32 v42, v42
	v_rcp_f32_e32 v43, v43
	v_rcp_f32_e32 v44, v44
	v_rcp_f32_e32 v45, v45
	v_cvt_pk_bf16_f32 v146, v46, v47
	v_cvt_pk_bf16_f32 v147, v48, v49
	v_cvt_pk_bf16_f32 v148, v42, v43
	v_cvt_pk_bf16_f32 v149, v44, v45
	global_store_dwordx4 v[176:177], v[146:149], off offset:2048
	v_pk_fma_f32 v[38:39], v[38:39], s[100:101], v[134:135]
	v_pk_fma_f32 v[40:41], v[40:41], s[100:101], v[136:137]
	v_pk_fma_f32 v[34:35], v[34:35], s[100:101], v[130:131]
	v_pk_fma_f32 v[36:37], v[36:37], s[100:101], v[132:133]
	v_exp_f32_e32 v38, v38
	v_exp_f32_e32 v39, v39
	v_exp_f32_e32 v40, v40
	v_exp_f32_e32 v41, v41
	v_exp_f32_e32 v34, v34
	v_exp_f32_e32 v35, v35
	v_exp_f32_e32 v36, v36
	v_exp_f32_e32 v37, v37
	v_pk_add_f32 v[38:39], v[38:39], 1.0 op_sel_hi:[1,0]
	v_pk_add_f32 v[40:41], v[40:41], 1.0 op_sel_hi:[1,0]
	v_pk_add_f32 v[34:35], v[34:35], 1.0 op_sel_hi:[1,0]
	v_pk_add_f32 v[36:37], v[36:37], 1.0 op_sel_hi:[1,0]
	v_rcp_f32_e32 v38, v38
	v_rcp_f32_e32 v39, v39
	v_rcp_f32_e32 v40, v40
	v_rcp_f32_e32 v41, v41
	v_rcp_f32_e32 v34, v34
	v_rcp_f32_e32 v35, v35
	v_rcp_f32_e32 v36, v36
	v_rcp_f32_e32 v37, v37
	v_cvt_pk_bf16_f32 v182, v38, v39
	v_cvt_pk_bf16_f32 v183, v40, v41
	v_cvt_pk_bf16_f32 v184, v34, v35
	v_cvt_pk_bf16_f32 v185, v36, v37
	global_store_dwordx4 v[176:177], v[182:185], off offset:3072
	v_lshl_add_u64 v[176:177], v[176:177], 0, s[14:15]
	v_pk_fma_f32 v[30:31], v[30:31], s[100:101], v[142:143]
	v_pk_fma_f32 v[32:33], v[32:33], s[100:101], v[144:145]
	v_pk_fma_f32 v[26:27], v[26:27], s[100:101], v[138:139]
	v_pk_fma_f32 v[28:29], v[28:29], s[100:101], v[140:141]
	v_exp_f32_e32 v30, v30
	v_exp_f32_e32 v31, v31
	v_exp_f32_e32 v32, v32
	v_exp_f32_e32 v33, v33
	v_exp_f32_e32 v26, v26
	v_exp_f32_e32 v27, v27
	v_exp_f32_e32 v28, v28
	v_exp_f32_e32 v29, v29
	v_pk_add_f32 v[30:31], v[30:31], 1.0 op_sel_hi:[1,0]
	v_pk_add_f32 v[32:33], v[32:33], 1.0 op_sel_hi:[1,0]
	v_pk_add_f32 v[26:27], v[26:27], 1.0 op_sel_hi:[1,0]
	v_pk_add_f32 v[28:29], v[28:29], 1.0 op_sel_hi:[1,0]
	v_rcp_f32_e32 v30, v30
	v_rcp_f32_e32 v31, v31
	v_rcp_f32_e32 v32, v32
	v_rcp_f32_e32 v33, v33
	v_rcp_f32_e32 v26, v26
	v_rcp_f32_e32 v27, v27
	v_rcp_f32_e32 v28, v28
	v_rcp_f32_e32 v29, v29
	v_cvt_pk_bf16_f32 v146, v30, v31
	v_cvt_pk_bf16_f32 v147, v32, v33
	v_cvt_pk_bf16_f32 v148, v26, v27
	v_cvt_pk_bf16_f32 v149, v28, v29
	global_store_dwordx4 v[176:177], v[146:149], off offset:0
	v_pk_fma_f32 v[22:23], v[22:23], s[100:101], v[134:135]
	v_pk_fma_f32 v[24:25], v[24:25], s[100:101], v[136:137]
	v_pk_fma_f32 v[18:19], v[18:19], s[100:101], v[130:131]
	v_pk_fma_f32 v[20:21], v[20:21], s[100:101], v[132:133]
	v_exp_f32_e32 v22, v22
	v_exp_f32_e32 v23, v23
	v_exp_f32_e32 v24, v24
	v_exp_f32_e32 v25, v25
	v_exp_f32_e32 v18, v18
	v_exp_f32_e32 v19, v19
	v_exp_f32_e32 v20, v20
	v_exp_f32_e32 v21, v21
	v_pk_add_f32 v[22:23], v[22:23], 1.0 op_sel_hi:[1,0]
	v_pk_add_f32 v[24:25], v[24:25], 1.0 op_sel_hi:[1,0]
	v_pk_add_f32 v[18:19], v[18:19], 1.0 op_sel_hi:[1,0]
	v_pk_add_f32 v[20:21], v[20:21], 1.0 op_sel_hi:[1,0]
	v_rcp_f32_e32 v22, v22
	v_rcp_f32_e32 v23, v23
	v_rcp_f32_e32 v24, v24
	v_rcp_f32_e32 v25, v25
	v_rcp_f32_e32 v18, v18
	v_rcp_f32_e32 v19, v19
	v_rcp_f32_e32 v20, v20
	v_rcp_f32_e32 v21, v21
	v_cvt_pk_bf16_f32 v182, v22, v23
	v_cvt_pk_bf16_f32 v183, v24, v25
	v_cvt_pk_bf16_f32 v184, v18, v19
	v_cvt_pk_bf16_f32 v185, v20, v21
	global_store_dwordx4 v[176:177], v[182:185], off offset:1024
	v_pk_fma_f32 v[14:15], v[14:15], s[100:101], v[142:143]
	v_pk_fma_f32 v[16:17], v[16:17], s[100:101], v[144:145]
	v_pk_fma_f32 v[10:11], v[10:11], s[100:101], v[138:139]
	v_pk_fma_f32 v[12:13], v[12:13], s[100:101], v[140:141]
	v_exp_f32_e32 v14, v14
	v_exp_f32_e32 v15, v15
	v_exp_f32_e32 v16, v16
	v_exp_f32_e32 v17, v17
	v_exp_f32_e32 v10, v10
	v_exp_f32_e32 v11, v11
	v_exp_f32_e32 v12, v12
	v_exp_f32_e32 v13, v13
	v_pk_add_f32 v[14:15], v[14:15], 1.0 op_sel_hi:[1,0]
	v_pk_add_f32 v[16:17], v[16:17], 1.0 op_sel_hi:[1,0]
	v_pk_add_f32 v[10:11], v[10:11], 1.0 op_sel_hi:[1,0]
	v_pk_add_f32 v[12:13], v[12:13], 1.0 op_sel_hi:[1,0]
	v_rcp_f32_e32 v14, v14
	v_rcp_f32_e32 v15, v15
	v_rcp_f32_e32 v16, v16
	v_rcp_f32_e32 v17, v17
	v_rcp_f32_e32 v10, v10
	v_rcp_f32_e32 v11, v11
	v_rcp_f32_e32 v12, v12
	v_rcp_f32_e32 v13, v13
	v_cvt_pk_bf16_f32 v146, v14, v15
	v_cvt_pk_bf16_f32 v147, v16, v17
	v_cvt_pk_bf16_f32 v148, v10, v11
	v_cvt_pk_bf16_f32 v149, v12, v13
	global_store_dwordx4 v[176:177], v[146:149], off offset:2048
	v_pk_fma_f32 v[6:7], v[6:7], s[100:101], v[134:135]
	v_pk_fma_f32 v[8:9], v[8:9], s[100:101], v[136:137]
	v_pk_fma_f32 v[2:3], v[2:3], s[100:101], v[130:131]
	v_pk_fma_f32 v[4:5], v[4:5], s[100:101], v[132:133]
	v_exp_f32_e32 v6, v6
	v_exp_f32_e32 v7, v7
	v_exp_f32_e32 v8, v8
	v_exp_f32_e32 v9, v9
	v_exp_f32_e32 v2, v2
	v_exp_f32_e32 v3, v3
	v_exp_f32_e32 v4, v4
	v_exp_f32_e32 v5, v5
	v_pk_add_f32 v[6:7], v[6:7], 1.0 op_sel_hi:[1,0]
	v_pk_add_f32 v[8:9], v[8:9], 1.0 op_sel_hi:[1,0]
	v_pk_add_f32 v[2:3], v[2:3], 1.0 op_sel_hi:[1,0]
	v_pk_add_f32 v[4:5], v[4:5], 1.0 op_sel_hi:[1,0]
	v_rcp_f32_e32 v6, v6
	v_rcp_f32_e32 v7, v7
	v_rcp_f32_e32 v8, v8
	v_rcp_f32_e32 v9, v9
	v_rcp_f32_e32 v2, v2
	v_rcp_f32_e32 v3, v3
	v_rcp_f32_e32 v4, v4
	v_rcp_f32_e32 v5, v5
	v_cvt_pk_bf16_f32 v182, v6, v7
	v_cvt_pk_bf16_f32 v183, v8, v9
	v_cvt_pk_bf16_f32 v184, v2, v3
	v_cvt_pk_bf16_f32 v185, v4, v5
	global_store_dwordx4 v[176:177], v[182:185], off offset:3072
	s_branch .LBB0_184
